# P1: bf16 copy of the sample rows of p moved from workgroups 0..31 (two GEMM units each) to 128..159 (one unit), grid 256 only
# speedup vs baseline: 1.0012x; 1.0012x over previous
; __device__ __forceinline__ unsigned pk2(float lo, float hi) { unsigned r; asm("v_cvt_pk_bf16_f32 %0, %1, %2" : "=v"(r) : "v"(lo), "v"(hi)); return r; }
; #define GIN(i) GPTR(const float, args.in[i])
; __global__ void __launch_bounds__(NWAVES * 64, 2) hymba_fwd(Args args) {
;     ...
;               const float* psm = GIN(I_PS) + (size_t)L * MS * PLE;
;               for (int e = e0; e < MS * (PLE / 8); e += NE) { const f32x4 a = *(const f32x4*)(psm + (size_t)e * 8), c = *(const f32x4*)(psm + (size_t)e * 8 + 4);
;                   v4u o; o.x = pk2(a[0], a[1]); o.y = pk2(a[2], a[3]); o.z = pk2(c[0], c[1]); o.w = pk2(c[2], c[3]); *(v4u*)(PB + (size_t)MP * PLE + (size_t)e * 8) = o; }
.LBB0_677:
	s_or_b64 exec, exec, s[0:1]
	v_readlane_b32 s68, v252, 10
	v_readlane_b32 s78, v252, 20
	v_readlane_b32 s79, v252, 21
	s_movk_i32 s0, 0x4000
	s_mov_b64 s[16:17], s[78:79]
	s_cmpk_lg_i32 s51, 0x100
	s_cbranch_scc1 .Lpsm_keep
	v_add_u32_e32 v4, 0xffff0000, v4
.Lpsm_keep:
	v_cmp_gt_u32_e32 vcc, s0, v4
	v_readlane_b32 s69, v252, 11
	v_readlane_b32 s70, v252, 12
	v_readlane_b32 s71, v252, 13
	v_readlane_b32 s72, v252, 14
	v_readlane_b32 s73, v252, 15
	v_readlane_b32 s74, v252, 16
	v_readlane_b32 s75, v252, 17
	v_readlane_b32 s76, v252, 18
	v_readlane_b32 s77, v252, 19
	v_readlane_b32 s80, v252, 22
	v_readlane_b32 s81, v252, 23
	v_readlane_b32 s82, v252, 24
	v_readlane_b32 s83, v252, 25
	s_and_saveexec_b64 s[0:1], vcc
	s_cbranch_execz .LBB0_184
	v_readlane_b32 s4, v253, 49
	v_readlane_b32 s5, v253, 50
	s_add_u32 s4, s16, s4
	s_addc_u32 s5, s17, s5
	v_lshlrev_b64 v[6:7], 5, v[4:5]
	v_lshl_add_u64 v[6:7], s[4:5], 0, v[6:7]
	v_readlane_b32 s4, v254, 28
	v_readlane_b32 s5, v254, 29
	v_lshl_add_u64 v[6:7], v[6:7], 0, 16
	s_mov_b64 s[16:17], 0
	v_lshl_add_u64 v[8:9], v[4:5], 4, s[4:5]
